# st7 + first-block conv input rows requested right after the X->LRU barrier (predicated copies before the loop instead of predicated loads mid-prologue)
# baseline (speedup 1.0000x reference)
.LBB0_215:
	s_waitcnt vmcnt(0)
	s_mov_b64 s[0:1], 0x1000
	v_lshl_add_u64 v[16:17], v[118:119], 0, s[0:1]
	v_lshl_add_u64 v[4:5], v[16:17], 0, v[2:3]
	v_mov_b64_e32 v[50:51], v[4:5]
	v_mov_b64_e32 v[8:9], v[150:151]
	v_readlane_b32 s4, v244, 0
	v_readlane_b32 s8, v244, 4
	v_readlane_b32 s9, v244, 5
	v_mov_b32_e32 v14, v130
	s_nop 1
	v_permlane16_swap_b32 v14, v130
	v_readlane_b32 s5, v244, 1
	v_readlane_b32 s6, v244, 2
	v_readlane_b32 s7, v244, 3
	v_readlane_b32 s4, v244, 57
	global_load_dwordx4 v[4:7], v114, s[8:9] offset:3072
	v_mov_b64_e32 v[52:53], v[152:153]
	v_mov_b64_e32 v[54:55], v[154:155]
	v_mov_b64_e32 v[56:57], v[156:157]
	global_load_dwordx4 v[58:61], v114, s[8:9] offset:3136
	global_load_dwordx4 v[62:65], v114, s[8:9] offset:3200
	global_load_dwordx4 v[66:69], v114, s[8:9] offset:3264
	v_mov_b64_e32 v[70:71], v[158:159]
	global_load_dwordx4 v[72:75], v114, s[8:9] offset:3328
	v_mov_b64_e32 v[76:77], v[160:161]
	v_mov_b64_e32 v[78:79], v[162:163]
	v_mov_b64_e32 v[80:81], v[164:165]
	global_load_dwordx4 v[82:85], v114, s[8:9] offset:3392
	global_load_dwordx4 v[86:89], v114, s[8:9] offset:3456
	global_load_dwordx4 v[90:93], v114, s[8:9] offset:3520
	v_mov_b64_e32 v[94:95], v[166:167]
	global_load_dwordx4 v[96:99], v114, s[8:9] offset:3584
	v_mov_b64_e32 v[100:101], v[168:169]
	v_mov_b64_e32 v[102:103], v[248:249]
	v_mov_b64_e32 v[104:105], v[250:251]
	global_load_dwordx4 v[106:109], v114, s[8:9] offset:3648
	global_load_dwordx4 v[120:123], v114, s[8:9] offset:3712
	global_load_dwordx4 v[124:127], v114, s[8:9] offset:3776
	v_mov_b64_e32 v[110:111], v[252:253]
	global_load_dwordx4 v[132:135], v114, s[8:9] offset:3840
	v_mov_b64_e32 v[136:137], v[254:255]
	global_load_dwordx2 v[138:139], v[50:51], off offset:448
	global_load_dwordx2 v[140:141], v[50:51], off offset:480
	global_load_dwordx4 v[142:145], v114, s[8:9] offset:3904
	global_load_dwordx4 v[146:149], v114, s[8:9] offset:3968
	global_load_dwordx4 v[150:153], v114, s[8:9] offset:4032
	v_readlane_b32 s24, v244, 16
	v_readlane_b32 s25, v244, 17
	v_readlane_b32 s26, v244, 42
	v_readlane_b32 s27, v244, 43
	v_readlane_b32 s28, v244, 44
	v_readlane_b32 s29, v244, 45
	v_readlane_b32 s30, v244, 10
	v_readlane_b32 s31, v244, 11
	v_readlane_b32 s32, v244, 14
	v_readlane_b32 s33, v244, 15
	v_readlane_b32 s34, v244, 48
	v_readlane_b32 s35, v244, 49
	v_lshlrev_b32_e32 v113, 2, v0
	v_and_b32_e32 v129, 63, v0
	v_lshrrev_b32_e32 v179, 6, v0
	v_lshlrev_b32_e32 v129, 4, v129
	v_add_u32_e32 v128, 0x1000, v113
	v_lshl_add_u32 v129, v179, 13, v129
	s_add_u32 s36, s34, 0x10000
	s_addc_u32 s37, s35, 0
	v_add_u32_e32 v179, 0x1000, v129
	global_load_dword v154, v113, s[24:25]
	global_load_dword v155, v113, s[26:27]
	global_load_dword v168, v113, s[26:27] offset:2048
	global_load_dword v169, v128, s[26:27]
	global_load_dword v171, v128, s[26:27] offset:2048
	global_load_dword v240, v113, s[28:29]
	global_load_dword v241, v113, s[30:31]
	global_load_dword v242, v113, s[32:33]
	global_load_dwordx4 v[156:159], v129, s[34:35]
	global_load_dwordx4 v[160:163], v129, s[34:35] offset:1024
	global_load_dwordx4 v[164:167], v129, s[34:35] offset:2048
	global_load_dwordx4 v[172:175], v129, s[34:35] offset:3072
	global_load_dwordx4 v[196:199], v129, s[36:37]
	global_load_dwordx4 v[200:203], v129, s[36:37] offset:1024
	global_load_dwordx4 v[204:207], v129, s[36:37] offset:2048
	global_load_dwordx4 v[208:211], v129, s[36:37] offset:3072
	global_load_dwordx4 v[212:215], v179, s[34:35]
	global_load_dwordx4 v[216:219], v179, s[36:37]
	global_load_dwordx4 v[220:223], v179, s[34:35] offset:1024
	global_load_dwordx4 v[224:227], v179, s[36:37] offset:1024
	global_load_dwordx4 v[228:231], v179, s[34:35] offset:2048
	global_load_dwordx4 v[232:235], v179, s[36:37] offset:2048
	global_load_dwordx4 v[236:239], v179, s[34:35] offset:3072
	global_load_dwordx4 v[248:251], v179, s[36:37] offset:3072
	s_waitcnt lgkmcnt(0)
	v_add_f32_e32 v14, v130, v14
	v_mov_b32_e32 v15, v14
	s_nop 1
	v_permlane32_swap_b32 v15, v14
	v_lshlrev_b64 v[10:11], 11, v[116:117]
	v_readlane_b32 s6, v244, 59
	v_readlane_b32 s7, v244, 60
	v_add_u32_e32 v12, s96, v131
	s_mov_b64 s[0:1], 0xdde0600
	v_or_b32_e32 v22, 32, v2
	v_mov_b32_e32 v23, v3
	v_or_b32_e32 v24, 64, v2
	v_mov_b32_e32 v25, v3
	v_or_b32_e32 v18, 0x60, v2
	v_mov_b32_e32 v19, v3
	v_lshl_add_u64 v[10:11], s[6:7], 0, v[10:11]
	s_waitcnt lgkmcnt(0)
	v_add_f32_e32 v14, v14, v15
	v_add3_u32 v26, v12, v115, v2
	v_lshl_add_u64 v[12:13], v[10:11], 0, s[0:1]
	v_lshl_add_u64 v[10:11], v[16:17], 0, v[22:23]
	v_lshl_add_u64 v[20:21], v[16:17], 0, v[24:25]
	v_lshl_add_u64 v[32:33], v[16:17], 0, v[18:19]
	v_fmamk_f32 v14, v14, 0x3b800000, v180
	s_mov_b32 s0, 0x800000
	ds_read2_b64 v[28:31], v26 offset1:4
	s_nop 0
	s_nop 0
	v_mul_f32_e32 v15, 0x4b800000, v14
	v_cmp_gt_f32_e32 vcc, s0, v14
	v_lshl_add_u64 v[34:35], v[12:13], 0, v[2:3]
	s_waitcnt lgkmcnt(0)
	v_lshlrev_b32_e32 v33, 16, v28
	v_cndmask_b32_e32 v14, v14, v15, vcc
	v_rsq_f32_e32 v14, v14
	v_and_b32_e32 v39, 0xffff0000, v28
	v_lshlrev_b32_e32 v41, 16, v29
	v_and_b32_e32 v29, 0xffff0000, v29
	v_mul_f32_e32 v15, 0x45800000, v14
	v_cndmask_b32_e32 v15, v14, v15, vcc
	v_lshl_add_u64 v[18:19], v[12:13], 0, v[18:19]
	v_mov_b32_e32 v44, v15
	v_mov_b32_e32 v46, v15
	v_mov_b32_e32 v48, v15
	v_readlane_b32 s36, v244, 10
	v_readlane_b32 s42, v244, 16
	v_readlane_b32 s43, v244, 17
	v_readlane_b32 s10, v244, 6
	v_readlane_b32 s11, v244, 7
	v_readlane_b32 s5, v244, 58
	s_movk_i32 s0, 0x1000
	v_readlane_b32 s37, v244, 11
	v_readlane_b32 s40, v244, 14
	v_readlane_b32 s41, v244, 15
	s_mov_b32 s3, 0x7f800000
	s_mov_b32 s2, 0x33800000
	v_readlane_b32 s38, v244, 12
	v_readlane_b32 s39, v244, 13
	v_readlane_b32 s44, v244, 18
	v_readlane_b32 s45, v244, 19
	v_readlane_b32 s46, v244, 20
	v_readlane_b32 s47, v244, 21
	v_readlane_b32 s48, v244, 22
	v_readlane_b32 s49, v244, 23
	v_readlane_b32 s50, v244, 24
	v_readlane_b32 s51, v244, 25
	v_lshlrev_b32_e32 v32, 16, v8
	v_and_b32_e32 v38, 0xffff0000, v8
	v_mul_f32_e32 v8, 0xbfb8aa3b, v32
	v_exp_f32_e32 v8, v8
	v_lshlrev_b32_e32 v40, 16, v9
	v_and_b32_e32 v28, 0xffff0000, v9
	v_mul_f32_e32 v9, 0xbfb8aa3b, v38
	v_exp_f32_e32 v9, v9
	v_add_f32_e32 v8, 1.0, v8
	v_rcp_f32_e32 v14, v8
	v_mul_f32_e32 v27, 0xbfb8aa3b, v40
	v_exp_f32_e32 v27, v27
	v_add_f32_e32 v43, 1.0, v9
	v_pk_mul_f32 v[8:9], v[14:15], v[32:33]
	v_rcp_f32_e32 v14, v43
	v_mul_f32_e32 v42, 0xbfb8aa3b, v28
	v_exp_f32_e32 v42, v42
	v_add_f32_e32 v27, 1.0, v27
	v_pk_mul_f32 v[32:33], v[14:15], v[38:39]
	v_rcp_f32_e32 v14, v27
	s_waitcnt vmcnt(41)
	v_mul_f32_e32 v4, v4, v9
	v_add_f32_e32 v42, 1.0, v42
	v_mul_f32_e32 v8, v8, v4
	v_mul_f32_e32 v4, v5, v33
	v_mul_f32_e32 v9, v32, v4
	v_pk_mul_f32 v[4:5], v[14:15], v[40:41]
	v_rcp_f32_e32 v14, v42
	v_mul_f32_e32 v5, v6, v5
	v_mul_f32_e32 v6, v4, v5
	v_cvt_pk_bf16_f32 v8, v8, v9
	v_pk_mul_f32 v[4:5], v[14:15], v[28:29]
	v_and_b32_e32 v29, 0xffff0000, v52
	v_mul_f32_e32 v5, v7, v5
	v_mul_f32_e32 v4, v4, v5
	v_cvt_pk_bf16_f32 v9, v6, v4
	global_store_dwordx2 v[34:35], v[8:9], off
	v_lshl_add_u64 v[8:9], v[12:13], 0, v[22:23]
	v_lshlrev_b32_e32 v23, 16, v52
	v_lshlrev_b32_e32 v22, 16, v30
	v_and_b32_e32 v28, 0xffff0000, v30
	v_lshlrev_b32_e32 v30, 16, v31
	v_and_b32_e32 v32, 0xffff0000, v31
	v_lshlrev_b32_e32 v31, 16, v53
	v_and_b32_e32 v33, 0xffff0000, v53
	v_mul_f32_e32 v10, 0xbfb8aa3b, v23
	v_mul_f32_e32 v11, 0xbfb8aa3b, v29
	v_mul_f32_e32 v14, 0xbfb8aa3b, v31
	v_mul_f32_e32 v27, 0xbfb8aa3b, v33
	v_exp_f32_e32 v10, v10
	v_exp_f32_e32 v11, v11
	v_exp_f32_e32 v14, v14
	v_exp_f32_e32 v27, v27
	v_add_f32_e32 v10, 1.0, v10
	v_add_f32_e32 v11, 1.0, v11
	v_add_f32_e32 v14, 1.0, v14
	v_add_f32_e32 v27, 1.0, v27
	v_rcp_f32_e32 v35, v10
	v_rcp_f32_e32 v39, v11
	v_rcp_f32_e32 v41, v14
	v_rcp_f32_e32 v43, v27
	v_mov_b32_e32 v34, v15
	v_mov_b32_e32 v38, v15
	v_mov_b32_e32 v40, v15
	v_mov_b32_e32 v42, v15
	v_pk_mul_f32 v[10:11], v[34:35], v[22:23]
	v_pk_mul_f32 v[22:23], v[38:39], v[28:29]
	v_pk_mul_f32 v[28:29], v[40:41], v[30:31]
	v_pk_mul_f32 v[30:31], v[42:43], v[32:33]
	v_mov_b32_e32 v32, v15
	s_waitcnt vmcnt(41)
	v_mul_f32_e32 v4, v58, v10
	v_mul_f32_e32 v5, v59, v22
	v_mul_f32_e32 v6, v60, v28
	v_mul_f32_e32 v7, v61, v30
	v_mul_f32_e32 v4, v4, v11
	v_mul_f32_e32 v5, v5, v23
	v_mul_f32_e32 v6, v6, v29
	v_mul_f32_e32 v7, v7, v31
	v_cvt_pk_bf16_f32 v4, v4, v5
	v_cvt_pk_bf16_f32 v5, v6, v7
	global_store_dwordx2 v[8:9], v[4:5], off
	ds_read2_b64 v[4:7], v26 offset0:8 offset1:12
	v_lshlrev_b32_e32 v29, 16, v55
	v_lshl_add_u64 v[22:23], v[12:13], 0, v[24:25]
	v_lshlrev_b32_e32 v25, 16, v54
	v_and_b32_e32 v31, 0xffff0000, v55
	s_waitcnt lgkmcnt(0)
	v_lshlrev_b32_e32 v28, 16, v5
	v_and_b32_e32 v30, 0xffff0000, v5
	v_and_b32_e32 v5, 0xffff0000, v54
	v_mul_f32_e32 v27, 0xbfb8aa3b, v5
	v_mul_f32_e32 v33, 0xbfb8aa3b, v29
	v_mul_f32_e32 v14, 0xbfb8aa3b, v25
	v_mul_f32_e32 v35, 0xbfb8aa3b, v31
	v_exp_f32_e32 v27, v27
	v_exp_f32_e32 v33, v33
	v_exp_f32_e32 v14, v14
	v_exp_f32_e32 v35, v35
	v_add_f32_e32 v27, 1.0, v27
	v_add_f32_e32 v36, 1.0, v33
	v_add_f32_e32 v14, 1.0, v14
	v_add_f32_e32 v37, 1.0, v35
	v_rcp_f32_e32 v35, v27
	v_rcp_f32_e32 v39, v36
	v_rcp_f32_e32 v33, v14
	v_rcp_f32_e32 v41, v37
	v_lshlrev_b32_e32 v24, 16, v4
	v_and_b32_e32 v4, 0xffff0000, v4
	v_pk_mul_f32 v[4:5], v[34:35], v[4:5]
	v_pk_mul_f32 v[28:29], v[38:39], v[28:29]
	v_pk_mul_f32 v[24:25], v[32:33], v[24:25]
	v_pk_mul_f32 v[30:31], v[40:41], v[30:31]
	v_mov_b32_e32 v36, v15
	s_waitcnt vmcnt(41)
	v_mul_f32_e32 v4, v63, v4
	v_mul_f32_e32 v9, v64, v28
	v_mul_f32_e32 v8, v62, v24
	v_mul_f32_e32 v10, v65, v30
	v_mul_f32_e32 v4, v4, v5
	v_mul_f32_e32 v5, v9, v29
	v_mul_f32_e32 v8, v8, v25
	v_mul_f32_e32 v9, v10, v31
	v_cvt_pk_bf16_f32 v4, v8, v4
	v_cvt_pk_bf16_f32 v5, v5, v9
	global_store_dwordx2 v[22:23], v[4:5], off
	v_or_b32_e32 v10, 0x80, v2
	v_mov_b32_e32 v11, v3
	v_lshl_add_u64 v[4:5], v[16:17], 0, v[10:11]
	v_lshlrev_b32_e32 v28, 16, v7
	v_and_b32_e32 v30, 0xffff0000, v7
	v_lshlrev_b32_e32 v5, 16, v56
	v_and_b32_e32 v7, 0xffff0000, v56
	v_lshlrev_b32_e32 v29, 16, v57
	v_and_b32_e32 v31, 0xffff0000, v57
	v_mul_f32_e32 v14, 0xbfb8aa3b, v5
	v_mul_f32_e32 v20, 0xbfb8aa3b, v7
	v_mul_f32_e32 v21, 0xbfb8aa3b, v29
	v_mul_f32_e32 v27, 0xbfb8aa3b, v31
	v_exp_f32_e32 v14, v14
	v_exp_f32_e32 v20, v20
	v_exp_f32_e32 v21, v21
	v_exp_f32_e32 v27, v27
	v_add_f32_e32 v14, 1.0, v14
	v_add_f32_e32 v20, 1.0, v20
	v_add_f32_e32 v21, 1.0, v21
	v_add_f32_e32 v27, 1.0, v27
	v_rcp_f32_e32 v33, v14
	v_rcp_f32_e32 v35, v20
	v_rcp_f32_e32 v37, v21
	v_rcp_f32_e32 v39, v27
	v_lshlrev_b32_e32 v4, 16, v6
	v_and_b32_e32 v6, 0xffff0000, v6
	v_pk_mul_f32 v[4:5], v[32:33], v[4:5]
	v_pk_mul_f32 v[6:7], v[34:35], v[6:7]
	v_pk_mul_f32 v[20:21], v[36:37], v[28:29]
	v_pk_mul_f32 v[28:29], v[38:39], v[30:31]
	v_lshl_add_u64 v[10:11], v[12:13], 0, v[10:11]
	s_waitcnt vmcnt(41)
	v_mul_f32_e32 v4, v66, v4
	v_mul_f32_e32 v6, v67, v6
	v_mul_f32_e32 v14, v68, v20
	v_mul_f32_e32 v20, v69, v28
	v_mul_f32_e32 v4, v4, v5
	v_mul_f32_e32 v5, v6, v7
	v_mul_f32_e32 v6, v14, v21
	v_mul_f32_e32 v7, v20, v29
	v_cvt_pk_bf16_f32 v4, v4, v5
	v_cvt_pk_bf16_f32 v5, v6, v7
	global_store_dwordx2 v[18:19], v[4:5], off
	ds_read2_b64 v[28:31], v26 offset0:16 offset1:20
	v_or_b32_e32 v22, 0xa0, v2
	v_mov_b32_e32 v23, v3
	v_or_b32_e32 v24, 0xc0, v2
	v_mov_b32_e32 v25, v3
	v_or_b32_e32 v18, 0xe0, v2
	v_mov_b32_e32 v19, v3
	v_lshl_add_u64 v[20:21], v[16:17], 0, v[22:23]
	v_lshl_add_u64 v[32:33], v[16:17], 0, v[24:25]
	v_lshl_add_u64 v[34:35], v[16:17], 0, v[18:19]
	s_nop 0
	s_nop 0
	s_waitcnt lgkmcnt(0)
	v_lshlrev_b32_e32 v38, 16, v29
	v_and_b32_e32 v40, 0xffff0000, v29
	v_lshlrev_b32_e32 v35, 16, v70
	v_and_b32_e32 v29, 0xffff0000, v70
	v_lshlrev_b32_e32 v39, 16, v71
	v_and_b32_e32 v41, 0xffff0000, v71
	v_mul_f32_e32 v8, 0xbfb8aa3b, v35
	v_mul_f32_e32 v9, 0xbfb8aa3b, v29
	v_mul_f32_e32 v14, 0xbfb8aa3b, v39
	v_mul_f32_e32 v27, 0xbfb8aa3b, v41
	v_exp_f32_e32 v8, v8
	v_exp_f32_e32 v9, v9
	v_exp_f32_e32 v14, v14
	v_exp_f32_e32 v27, v27
	v_add_f32_e32 v8, 1.0, v8
	v_add_f32_e32 v9, 1.0, v9
	v_add_f32_e32 v14, 1.0, v14
	v_add_f32_e32 v27, 1.0, v27
	v_rcp_f32_e32 v43, v8
	v_rcp_f32_e32 v45, v9
	v_rcp_f32_e32 v47, v14
	v_rcp_f32_e32 v49, v27
	v_lshlrev_b32_e32 v34, 16, v28
	v_and_b32_e32 v28, 0xffff0000, v28
	v_pk_mul_f32 v[8:9], v[42:43], v[34:35]
	v_pk_mul_f32 v[28:29], v[44:45], v[28:29]
	v_pk_mul_f32 v[34:35], v[46:47], v[38:39]
	v_pk_mul_f32 v[38:39], v[48:49], v[40:41]
	v_mov_b32_e32 v40, v15
	v_lshl_add_u64 v[18:19], v[12:13], 0, v[18:19]
	s_waitcnt vmcnt(41)
	v_mul_f32_e32 v4, v72, v8
	v_mul_f32_e32 v5, v73, v28
	v_mul_f32_e32 v6, v74, v34
	v_mul_f32_e32 v7, v75, v38
	v_mul_f32_e32 v4, v4, v9
	v_mul_f32_e32 v5, v5, v29
	v_mul_f32_e32 v6, v6, v35
	v_mul_f32_e32 v7, v7, v39
	v_cvt_pk_bf16_f32 v4, v4, v5
	v_cvt_pk_bf16_f32 v5, v6, v7
	global_store_dwordx2 v[10:11], v[4:5], off
	v_lshl_add_u64 v[8:9], v[12:13], 0, v[22:23]
	v_lshlrev_b32_e32 v11, 16, v76
	v_and_b32_e32 v23, 0xffff0000, v76
	v_lshlrev_b32_e32 v10, 16, v30
	v_and_b32_e32 v22, 0xffff0000, v30
	v_lshlrev_b32_e32 v28, 16, v31
	v_and_b32_e32 v30, 0xffff0000, v31
	v_lshlrev_b32_e32 v29, 16, v77
	v_and_b32_e32 v31, 0xffff0000, v77
	v_mul_f32_e32 v14, 0xbfb8aa3b, v11
	v_mul_f32_e32 v27, 0xbfb8aa3b, v23
	v_mul_f32_e32 v35, 0xbfb8aa3b, v29
	v_mul_f32_e32 v36, 0xbfb8aa3b, v31
	v_exp_f32_e32 v14, v14
	v_exp_f32_e32 v27, v27
	v_exp_f32_e32 v35, v35
	v_exp_f32_e32 v36, v36
	v_add_f32_e32 v14, 1.0, v14
	v_add_f32_e32 v27, 1.0, v27
	v_add_f32_e32 v37, 1.0, v35
	v_add_f32_e32 v36, 1.0, v36
	v_rcp_f32_e32 v35, v14
	v_rcp_f32_e32 v39, v27
	v_rcp_f32_e32 v41, v37
	v_rcp_f32_e32 v43, v36
	v_mov_b32_e32 v34, v15
	v_mov_b32_e32 v38, v15
	v_pk_mul_f32 v[10:11], v[34:35], v[10:11]
	v_pk_mul_f32 v[22:23], v[38:39], v[22:23]
	v_pk_mul_f32 v[28:29], v[40:41], v[28:29]
	v_pk_mul_f32 v[30:31], v[42:43], v[30:31]
	v_mov_b32_e32 v36, v15
	s_waitcnt vmcnt(41)
	v_mul_f32_e32 v4, v82, v10
	v_mul_f32_e32 v5, v83, v22
	v_mul_f32_e32 v6, v84, v28
	v_mul_f32_e32 v7, v85, v30
	v_mul_f32_e32 v4, v4, v11
	v_mul_f32_e32 v5, v5, v23
	v_mul_f32_e32 v6, v6, v29
	v_mul_f32_e32 v7, v7, v31
	v_cvt_pk_bf16_f32 v4, v4, v5
	v_cvt_pk_bf16_f32 v5, v6, v7
	global_store_dwordx2 v[8:9], v[4:5], off
	ds_read2_b64 v[4:7], v26 offset0:24 offset1:28
	v_lshlrev_b32_e32 v29, 16, v79
	v_lshl_add_u64 v[22:23], v[12:13], 0, v[24:25]
	v_lshlrev_b32_e32 v25, 16, v78
	v_and_b32_e32 v31, 0xffff0000, v79
	s_waitcnt lgkmcnt(0)
	v_lshlrev_b32_e32 v28, 16, v5
	v_and_b32_e32 v30, 0xffff0000, v5
	v_and_b32_e32 v5, 0xffff0000, v78
	v_mul_f32_e32 v27, 0xbfb8aa3b, v5
	v_mul_f32_e32 v32, 0xbfb8aa3b, v29
	v_mul_f32_e32 v14, 0xbfb8aa3b, v25
	v_mul_f32_e32 v33, 0xbfb8aa3b, v31
	v_exp_f32_e32 v27, v27
	v_exp_f32_e32 v32, v32
	v_exp_f32_e32 v14, v14
	v_exp_f32_e32 v33, v33
	v_add_f32_e32 v27, 1.0, v27
	v_add_f32_e32 v32, 1.0, v32
	v_add_f32_e32 v14, 1.0, v14
	v_add_f32_e32 v33, 1.0, v33
	v_rcp_f32_e32 v37, v27
	v_rcp_f32_e32 v39, v32
	v_rcp_f32_e32 v35, v14
	v_rcp_f32_e32 v41, v33
	v_lshlrev_b32_e32 v24, 16, v4
	v_and_b32_e32 v4, 0xffff0000, v4
	v_pk_mul_f32 v[4:5], v[36:37], v[4:5]
	v_pk_mul_f32 v[28:29], v[38:39], v[28:29]
	v_pk_mul_f32 v[24:25], v[34:35], v[24:25]
	v_pk_mul_f32 v[30:31], v[40:41], v[30:31]
	v_mov_b32_e32 v32, v15
	s_waitcnt vmcnt(41)
	v_mul_f32_e32 v4, v87, v4
	v_mul_f32_e32 v9, v88, v28
	v_mul_f32_e32 v8, v86, v24
	v_mul_f32_e32 v10, v89, v30
	v_mul_f32_e32 v4, v4, v5
	v_mul_f32_e32 v5, v9, v29
	v_mul_f32_e32 v8, v8, v25
	v_mul_f32_e32 v9, v10, v31
	v_cvt_pk_bf16_f32 v4, v8, v4
	v_cvt_pk_bf16_f32 v5, v5, v9
	global_store_dwordx2 v[22:23], v[4:5], off
	v_or_b32_e32 v10, 0x100, v2
	v_mov_b32_e32 v11, v3
	v_lshl_add_u64 v[4:5], v[16:17], 0, v[10:11]
	v_lshlrev_b32_e32 v28, 16, v7
	v_and_b32_e32 v30, 0xffff0000, v7
	v_lshlrev_b32_e32 v5, 16, v80
	v_and_b32_e32 v7, 0xffff0000, v80
	v_lshlrev_b32_e32 v29, 16, v81
	v_and_b32_e32 v31, 0xffff0000, v81
	v_mul_f32_e32 v14, 0xbfb8aa3b, v5
	v_mul_f32_e32 v20, 0xbfb8aa3b, v7
	v_mul_f32_e32 v21, 0xbfb8aa3b, v29
	v_mul_f32_e32 v27, 0xbfb8aa3b, v31
	v_exp_f32_e32 v14, v14
	v_exp_f32_e32 v20, v20
	v_exp_f32_e32 v21, v21
	v_exp_f32_e32 v27, v27
	v_add_f32_e32 v14, 1.0, v14
	v_add_f32_e32 v20, 1.0, v20
	v_add_f32_e32 v21, 1.0, v21
	v_add_f32_e32 v27, 1.0, v27
	v_rcp_f32_e32 v33, v14
	v_rcp_f32_e32 v35, v20
	v_rcp_f32_e32 v37, v21
	v_rcp_f32_e32 v39, v27
	v_lshlrev_b32_e32 v4, 16, v6
	v_and_b32_e32 v6, 0xffff0000, v6
	v_pk_mul_f32 v[4:5], v[32:33], v[4:5]
	v_pk_mul_f32 v[6:7], v[34:35], v[6:7]
	v_pk_mul_f32 v[20:21], v[36:37], v[28:29]
	v_pk_mul_f32 v[28:29], v[38:39], v[30:31]
	v_lshl_add_u64 v[36:37], v[12:13], 0, v[10:11]
	s_waitcnt vmcnt(41)
	v_mul_f32_e32 v4, v90, v4
	v_mul_f32_e32 v6, v91, v6
	v_mul_f32_e32 v14, v92, v20
	v_mul_f32_e32 v20, v93, v28
	v_mul_f32_e32 v4, v4, v5
	v_mul_f32_e32 v5, v6, v7
	v_mul_f32_e32 v6, v14, v21
	v_mul_f32_e32 v7, v20, v29
	v_cvt_pk_bf16_f32 v4, v4, v5
	v_cvt_pk_bf16_f32 v5, v6, v7
	global_store_dwordx2 v[18:19], v[4:5], off
	ds_read2_b64 v[28:31], v26 offset0:32 offset1:36
	v_or_b32_e32 v20, 0x120, v2
	v_mov_b32_e32 v21, v3
	v_or_b32_e32 v22, 0x140, v2
	v_mov_b32_e32 v23, v3
	v_or_b32_e32 v18, 0x160, v2
	v_mov_b32_e32 v19, v3
	v_lshl_add_u64 v[24:25], v[16:17], 0, v[20:21]
	v_lshl_add_u64 v[32:33], v[16:17], 0, v[22:23]
	v_lshl_add_u64 v[34:35], v[16:17], 0, v[18:19]
	s_nop 0
	s_nop 0
	s_waitcnt lgkmcnt(0)
	v_lshlrev_b32_e32 v38, 16, v29
	v_and_b32_e32 v40, 0xffff0000, v29
	v_lshlrev_b32_e32 v35, 16, v94
	v_and_b32_e32 v29, 0xffff0000, v94
	v_lshlrev_b32_e32 v39, 16, v95
	v_and_b32_e32 v41, 0xffff0000, v95
	v_mul_f32_e32 v8, 0xbfb8aa3b, v35
	v_mul_f32_e32 v9, 0xbfb8aa3b, v29
	v_mul_f32_e32 v14, 0xbfb8aa3b, v39
	v_mul_f32_e32 v27, 0xbfb8aa3b, v41
	v_exp_f32_e32 v8, v8
	v_exp_f32_e32 v9, v9
	v_exp_f32_e32 v14, v14
	v_exp_f32_e32 v27, v27
	v_add_f32_e32 v8, 1.0, v8
	v_add_f32_e32 v9, 1.0, v9
	v_add_f32_e32 v14, 1.0, v14
	v_add_f32_e32 v27, 1.0, v27
	v_rcp_f32_e32 v43, v8
	v_rcp_f32_e32 v45, v9
	v_rcp_f32_e32 v47, v14
	v_rcp_f32_e32 v49, v27
	v_lshlrev_b32_e32 v34, 16, v28
	v_and_b32_e32 v28, 0xffff0000, v28
	v_pk_mul_f32 v[8:9], v[42:43], v[34:35]
	v_pk_mul_f32 v[28:29], v[44:45], v[28:29]
	v_pk_mul_f32 v[34:35], v[46:47], v[38:39]
	v_pk_mul_f32 v[38:39], v[48:49], v[40:41]
	v_mov_b32_e32 v40, v15
	s_waitcnt vmcnt(41)
	v_mul_f32_e32 v4, v96, v8
	v_mul_f32_e32 v5, v97, v28
	v_mul_f32_e32 v6, v98, v34
	v_mul_f32_e32 v7, v99, v38
	v_mul_f32_e32 v4, v4, v9
	v_mul_f32_e32 v5, v5, v29
	v_mul_f32_e32 v6, v6, v35
	v_mul_f32_e32 v7, v7, v39
	v_cvt_pk_bf16_f32 v4, v4, v5
	v_cvt_pk_bf16_f32 v5, v6, v7
	global_store_dwordx2 v[36:37], v[4:5], off
	v_lshl_add_u64 v[8:9], v[12:13], 0, v[20:21]
	v_lshlrev_b32_e32 v21, 16, v100
	v_and_b32_e32 v29, 0xffff0000, v100
	v_lshlrev_b32_e32 v20, 16, v30
	v_and_b32_e32 v28, 0xffff0000, v30
	v_lshlrev_b32_e32 v30, 16, v31
	v_and_b32_e32 v34, 0xffff0000, v31
	v_lshlrev_b32_e32 v31, 16, v101
	v_and_b32_e32 v35, 0xffff0000, v101
	v_mul_f32_e32 v14, 0xbfb8aa3b, v21
	v_mul_f32_e32 v24, 0xbfb8aa3b, v29
	v_mul_f32_e32 v25, 0xbfb8aa3b, v31
	v_mul_f32_e32 v27, 0xbfb8aa3b, v35
	v_exp_f32_e32 v14, v14
	v_exp_f32_e32 v24, v24
	v_exp_f32_e32 v25, v25
	v_exp_f32_e32 v27, v27
	v_add_f32_e32 v14, 1.0, v14
	v_add_f32_e32 v24, 1.0, v24
	v_add_f32_e32 v25, 1.0, v25
	v_add_f32_e32 v27, 1.0, v27
	v_rcp_f32_e32 v37, v14
	v_rcp_f32_e32 v39, v24
	v_rcp_f32_e32 v41, v25
	v_rcp_f32_e32 v43, v27
	v_mov_b32_e32 v36, v15
	v_mov_b32_e32 v38, v15
	v_pk_mul_f32 v[20:21], v[36:37], v[20:21]
	v_pk_mul_f32 v[24:25], v[38:39], v[28:29]
	v_pk_mul_f32 v[28:29], v[40:41], v[30:31]
	v_pk_mul_f32 v[30:31], v[42:43], v[34:35]
	v_mov_b32_e32 v34, v15
	s_waitcnt vmcnt(41)
	v_mul_f32_e32 v4, v106, v20
	v_mul_f32_e32 v5, v107, v24
	v_mul_f32_e32 v6, v108, v28
	v_mul_f32_e32 v7, v109, v30
	v_mul_f32_e32 v4, v4, v21
	v_mul_f32_e32 v5, v5, v25
	v_mul_f32_e32 v6, v6, v29
	v_mul_f32_e32 v7, v7, v31
	v_cvt_pk_bf16_f32 v4, v4, v5
	v_cvt_pk_bf16_f32 v5, v6, v7
	global_store_dwordx2 v[8:9], v[4:5], off
	ds_read2_b64 v[4:7], v26 offset0:40 offset1:44
	v_lshl_add_u64 v[8:9], v[12:13], 0, v[22:23]
	v_lshlrev_b32_e32 v21, 16, v102
	v_lshlrev_b32_e32 v23, 16, v103
	v_and_b32_e32 v25, 0xffff0000, v103
	s_waitcnt lgkmcnt(0)
	v_lshlrev_b32_e32 v22, 16, v5
	v_and_b32_e32 v24, 0xffff0000, v5
	v_and_b32_e32 v5, 0xffff0000, v102
	v_mul_f32_e32 v14, 0xbfb8aa3b, v21
	v_mul_f32_e32 v27, 0xbfb8aa3b, v5
	v_mul_f32_e32 v32, 0xbfb8aa3b, v23
	v_mul_f32_e32 v33, 0xbfb8aa3b, v25
	v_exp_f32_e32 v14, v14
	v_exp_f32_e32 v27, v27
	v_exp_f32_e32 v32, v32
	v_exp_f32_e32 v33, v33
	v_add_f32_e32 v14, 1.0, v14
	v_add_f32_e32 v27, 1.0, v27
	v_add_f32_e32 v32, 1.0, v32
	v_add_f32_e32 v33, 1.0, v33
	v_rcp_f32_e32 v35, v14
	v_rcp_f32_e32 v37, v27
	v_rcp_f32_e32 v39, v32
	v_rcp_f32_e32 v41, v33
	v_lshlrev_b32_e32 v20, 16, v4
	v_and_b32_e32 v4, 0xffff0000, v4
	v_pk_mul_f32 v[20:21], v[34:35], v[20:21]
	v_pk_mul_f32 v[4:5], v[36:37], v[4:5]
	v_pk_mul_f32 v[22:23], v[38:39], v[22:23]
	v_pk_mul_f32 v[24:25], v[40:41], v[24:25]
	v_mov_b32_e32 v32, v15
	s_waitcnt vmcnt(41)
	v_mul_f32_e32 v14, v120, v20
	v_mul_f32_e32 v4, v121, v4
	v_mul_f32_e32 v20, v122, v22
	v_mul_f32_e32 v22, v123, v24
	v_mul_f32_e32 v4, v4, v5
	v_mul_f32_e32 v5, v20, v23
	v_mul_f32_e32 v14, v14, v21
	v_mul_f32_e32 v20, v22, v25
	v_cvt_pk_bf16_f32 v4, v14, v4
	v_cvt_pk_bf16_f32 v5, v5, v20
	global_store_dwordx2 v[8:9], v[4:5], off
	v_or_b32_e32 v20, 0x180, v2
	v_mov_b32_e32 v21, v3
	v_lshl_add_u64 v[4:5], v[16:17], 0, v[20:21]
	v_lshl_add_u64 v[8:9], v[12:13], 0, v[18:19]
	v_lshlrev_b32_e32 v28, 16, v7
	v_and_b32_e32 v30, 0xffff0000, v7
	v_lshlrev_b32_e32 v5, 16, v104
	v_and_b32_e32 v7, 0xffff0000, v104
	v_lshlrev_b32_e32 v29, 16, v105
	v_and_b32_e32 v31, 0xffff0000, v105
	v_mul_f32_e32 v10, 0xbfb8aa3b, v5
	v_mul_f32_e32 v11, 0xbfb8aa3b, v7
	v_mul_f32_e32 v14, 0xbfb8aa3b, v29
	v_mul_f32_e32 v27, 0xbfb8aa3b, v31
	v_exp_f32_e32 v10, v10
	v_exp_f32_e32 v11, v11
	v_exp_f32_e32 v14, v14
	v_exp_f32_e32 v27, v27
	v_add_f32_e32 v10, 1.0, v10
	v_add_f32_e32 v11, 1.0, v11
	v_add_f32_e32 v14, 1.0, v14
	v_add_f32_e32 v27, 1.0, v27
	v_rcp_f32_e32 v33, v10
	v_rcp_f32_e32 v35, v11
	v_rcp_f32_e32 v37, v14
	v_rcp_f32_e32 v39, v27
	v_lshlrev_b32_e32 v4, 16, v6
	v_and_b32_e32 v6, 0xffff0000, v6
	v_pk_mul_f32 v[4:5], v[32:33], v[4:5]
	v_pk_mul_f32 v[6:7], v[34:35], v[6:7]
	v_pk_mul_f32 v[10:11], v[36:37], v[28:29]
	v_pk_mul_f32 v[28:29], v[38:39], v[30:31]
	v_lshl_add_u64 v[20:21], v[12:13], 0, v[20:21]
	s_waitcnt vmcnt(41)
	v_mul_f32_e32 v4, v124, v4
	v_mul_f32_e32 v6, v125, v6
	v_mul_f32_e32 v10, v126, v10
	v_mul_f32_e32 v14, v127, v28
	v_mul_f32_e32 v4, v4, v5
	v_mul_f32_e32 v5, v6, v7
	v_mul_f32_e32 v6, v10, v11
	v_mul_f32_e32 v7, v14, v29
	v_cvt_pk_bf16_f32 v4, v4, v5
	v_cvt_pk_bf16_f32 v5, v6, v7
	global_store_dwordx2 v[8:9], v[4:5], off
	ds_read2_b64 v[8:11], v26 offset0:48 offset1:52
	v_lshlrev_b32_e32 v33, 16, v110
	v_lshlrev_b32_e32 v35, 16, v111
	v_and_b32_e32 v37, 0xffff0000, v111
	v_mul_f32_e32 v14, 0xbfb8aa3b, v33
	s_waitcnt lgkmcnt(0)
	v_lshlrev_b32_e32 v34, 16, v9
	v_and_b32_e32 v36, 0xffff0000, v9
	v_and_b32_e32 v9, 0xffff0000, v110
	v_mul_f32_e32 v18, 0xbfb8aa3b, v9
	v_mul_f32_e32 v19, 0xbfb8aa3b, v35
	v_mul_f32_e32 v27, 0xbfb8aa3b, v37
	v_exp_f32_e32 v14, v14
	v_exp_f32_e32 v18, v18
	v_or_b32_e32 v22, 0x1a0, v2
	v_mov_b32_e32 v23, v3
	v_or_b32_e32 v24, 0x1c0, v2
	v_mov_b32_e32 v25, v3
	v_or_b32_e32 v2, 0x1e0, v2
	v_exp_f32_e32 v19, v19
	v_exp_f32_e32 v27, v27
	v_lshl_add_u64 v[28:29], v[16:17], 0, v[22:23]
	v_lshl_add_u64 v[30:31], v[16:17], 0, v[24:25]
	v_lshl_add_u64 v[16:17], v[16:17], 0, v[2:3]
	s_nop 0
	s_nop 0
	v_add_f32_e32 v14, 1.0, v14
	v_add_f32_e32 v18, 1.0, v18
	v_add_f32_e32 v19, 1.0, v19
	v_add_f32_e32 v27, 1.0, v27
	v_rcp_f32_e32 v39, v14
	v_rcp_f32_e32 v41, v18
	v_rcp_f32_e32 v43, v19
	v_rcp_f32_e32 v45, v27
	v_lshlrev_b32_e32 v32, 16, v8
	v_and_b32_e32 v8, 0xffff0000, v8
	v_pk_mul_f32 v[18:19], v[38:39], v[32:33]
	v_pk_mul_f32 v[8:9], v[40:41], v[8:9]
	v_pk_mul_f32 v[32:33], v[42:43], v[34:35]
	v_pk_mul_f32 v[34:35], v[44:45], v[36:37]
	v_mov_b32_e32 v36, v15
	v_mov_b32_e32 v42, v0
	s_waitcnt vmcnt(41)
	v_mul_f32_e32 v4, v132, v18
	v_mul_f32_e32 v5, v133, v8
	v_mul_f32_e32 v6, v134, v32
	v_mul_f32_e32 v7, v135, v34
	v_mul_f32_e32 v4, v4, v19
	v_mul_f32_e32 v5, v5, v9
	v_mul_f32_e32 v6, v6, v33
	v_mul_f32_e32 v7, v7, v35
	v_cvt_pk_bf16_f32 v4, v4, v5
	v_cvt_pk_bf16_f32 v5, v6, v7
	global_store_dwordx2 v[20:21], v[4:5], off
	v_lshl_add_u64 v[8:9], v[12:13], 0, v[22:23]
	v_lshlrev_b32_e32 v20, 16, v11
	v_and_b32_e32 v22, 0xffff0000, v11
	v_lshlrev_b32_e32 v18, 16, v10
	v_and_b32_e32 v10, 0xffff0000, v10
	v_mov_b32_e32 v32, v15
	v_mov_b32_e32 v34, v15
	v_lshlrev_b32_e32 v19, 16, v136
	v_and_b32_e32 v11, 0xffff0000, v136
	v_lshlrev_b32_e32 v21, 16, v137
	v_and_b32_e32 v23, 0xffff0000, v137
	v_mul_f32_e32 v14, 0xbfb8aa3b, v19
	v_mul_f32_e32 v27, 0xbfb8aa3b, v11
	v_mul_f32_e32 v28, 0xbfb8aa3b, v21
	v_mul_f32_e32 v29, 0xbfb8aa3b, v23
	v_exp_f32_e32 v14, v14
	v_exp_f32_e32 v27, v27
	v_exp_f32_e32 v28, v28
	v_exp_f32_e32 v29, v29
	v_add_f32_e32 v14, 1.0, v14
	v_add_f32_e32 v27, 1.0, v27
	v_add_f32_e32 v28, 1.0, v28
	v_add_f32_e32 v29, 1.0, v29
	v_rcp_f32_e32 v33, v14
	v_rcp_f32_e32 v35, v27
	v_rcp_f32_e32 v37, v28
	v_rcp_f32_e32 v39, v29
	v_pk_mul_f32 v[18:19], v[32:33], v[18:19]
	v_pk_mul_f32 v[10:11], v[34:35], v[10:11]
	v_pk_mul_f32 v[20:21], v[36:37], v[20:21]
	v_pk_mul_f32 v[22:23], v[38:39], v[22:23]
	v_mov_b32_e32 v28, v15
	s_waitcnt vmcnt(39)
	v_mul_f32_e32 v4, v142, v18
	v_mul_f32_e32 v5, v143, v10
	v_mul_f32_e32 v6, v144, v20
	v_mul_f32_e32 v7, v145, v22
	v_mul_f32_e32 v4, v4, v19
	v_mul_f32_e32 v5, v5, v11
	v_mul_f32_e32 v6, v6, v21
	v_mul_f32_e32 v7, v7, v23
	v_cvt_pk_bf16_f32 v4, v4, v5
	v_cvt_pk_bf16_f32 v5, v6, v7
	global_store_dwordx2 v[8:9], v[4:5], off
	ds_read2_b64 v[4:7], v26 offset0:56 offset1:60
	v_lshl_add_u64 v[18:19], v[12:13], 0, v[24:25]
	v_lshlrev_b32_e32 v23, 16, v139
	v_lshlrev_b32_e32 v21, 16, v138
	v_and_b32_e32 v25, 0xffff0000, v139
	s_waitcnt lgkmcnt(0)
	v_lshlrev_b32_e32 v22, 16, v5
	v_and_b32_e32 v24, 0xffff0000, v5
	v_and_b32_e32 v5, 0xffff0000, v138
	v_mul_f32_e32 v27, 0xbfb8aa3b, v5
	v_mul_f32_e32 v29, 0xbfb8aa3b, v23
	v_mul_f32_e32 v14, 0xbfb8aa3b, v21
	v_mul_f32_e32 v30, 0xbfb8aa3b, v25
	v_exp_f32_e32 v27, v27
	v_exp_f32_e32 v29, v29
	v_exp_f32_e32 v14, v14
	v_exp_f32_e32 v30, v30
	v_add_f32_e32 v31, 1.0, v27
	v_add_f32_e32 v33, 1.0, v29
	v_add_f32_e32 v14, 1.0, v14
	v_add_f32_e32 v30, 1.0, v30
	v_rcp_f32_e32 v29, v31
	v_rcp_f32_e32 v33, v33
	v_rcp_f32_e32 v27, v14
	v_rcp_f32_e32 v35, v30
	v_lshlrev_b32_e32 v20, 16, v4
	v_and_b32_e32 v4, 0xffff0000, v4
	v_mov_b32_e32 v26, v15
	v_pk_mul_f32 v[4:5], v[28:29], v[4:5]
	v_pk_mul_f32 v[22:23], v[32:33], v[22:23]
	v_pk_mul_f32 v[20:21], v[26:27], v[20:21]
	v_pk_mul_f32 v[24:25], v[34:35], v[24:25]
	v_lshlrev_b32_e32 v14, 16, v7
	s_waitcnt vmcnt(39)
	v_mul_f32_e32 v4, v147, v4
	v_mul_f32_e32 v9, v148, v22
	v_mul_f32_e32 v8, v146, v20
	v_mul_f32_e32 v10, v149, v24
	v_mul_f32_e32 v4, v4, v5
	v_mul_f32_e32 v5, v9, v23
	v_mul_f32_e32 v8, v8, v21
	v_mul_f32_e32 v9, v10, v25
	v_cvt_pk_bf16_f32 v4, v8, v4
	v_cvt_pk_bf16_f32 v5, v5, v9
	global_store_dwordx2 v[18:19], v[4:5], off
	v_lshl_add_u64 v[4:5], v[12:13], 0, v[2:3]
	v_and_b32_e32 v18, 0xffff0000, v7
	v_mov_b32_e32 v20, v15
	v_mov_b32_e32 v22, v15
	v_mov_b32_e32 v24, v15
	v_lshlrev_b32_e32 v13, 16, v140
	v_and_b32_e32 v7, 0xffff0000, v140
	v_lshlrev_b32_e32 v15, 16, v141
	v_and_b32_e32 v19, 0xffff0000, v141
	v_mul_f32_e32 v2, 0xbfb8aa3b, v13
	v_mul_f32_e32 v16, 0xbfb8aa3b, v7
	v_mul_f32_e32 v17, 0xbfb8aa3b, v15
	v_mul_f32_e32 v21, 0xbfb8aa3b, v19
	v_exp_f32_e32 v2, v2
	v_exp_f32_e32 v16, v16
	v_exp_f32_e32 v17, v17
	v_exp_f32_e32 v21, v21
	v_add_f32_e32 v2, 1.0, v2
	v_add_f32_e32 v16, 1.0, v16
	v_add_f32_e32 v17, 1.0, v17
	v_add_f32_e32 v27, 1.0, v21
	v_rcp_f32_e32 v21, v2
	v_rcp_f32_e32 v23, v16
	v_rcp_f32_e32 v25, v17
	v_rcp_f32_e32 v27, v27
	v_lshlrev_b32_e32 v12, 16, v6
	v_and_b32_e32 v6, 0xffff0000, v6
	v_pk_mul_f32 v[12:13], v[20:21], v[12:13]
	v_pk_mul_f32 v[6:7], v[22:23], v[6:7]
	v_pk_mul_f32 v[14:15], v[24:25], v[14:15]
	v_pk_mul_f32 v[16:17], v[26:27], v[18:19]
	v_readlane_b32 s4, v244, 32
	v_readlane_b32 s14, v244, 42
	v_readlane_b32 s15, v244, 43
	v_readlane_b32 s16, v244, 44
	v_readlane_b32 s17, v244, 45
	v_readlane_b32 s6, v244, 34
	s_mov_b32 s6, 0xbfb8aa3b
	s_mov_b32 s4, 0x3f2aaaab
	v_readlane_b32 s5, v244, 33
	s_mov_b32 s5, 0x3f317218
	v_readlane_b32 s7, v244, 35
	v_readlane_b32 s8, v244, 36
	v_readlane_b32 s9, v244, 37
	v_readlane_b32 s10, v244, 38
	v_readlane_b32 s11, v244, 39
	v_readlane_b32 s12, v244, 40
	v_readlane_b32 s13, v244, 41
	v_readlane_b32 s18, v244, 46
	v_readlane_b32 s19, v244, 47
	s_waitcnt vmcnt(39)
	v_mul_f32_e32 v2, v150, v12
	v_mul_f32_e32 v6, v151, v6
	v_mul_f32_e32 v8, v152, v14
	v_mul_f32_e32 v9, v153, v16
	v_mul_f32_e32 v6, v6, v7
	v_mul_f32_e32 v7, v8, v15
	v_mul_f32_e32 v2, v2, v13
	v_mul_f32_e32 v8, v9, v17
	v_cvt_pk_bf16_f32 v6, v2, v6
	v_cvt_pk_bf16_f32 v7, v7, v8
	global_store_dwordx2 v[4:5], v[6:7], off
	s_barrier
	s_waitcnt vmcnt(32)
	s_nop 0
	v_ashrrev_i32_e32 v43, 31, v42
	v_lshlrev_b64 v[4:5], 2, v[42:43]
	v_lshl_add_u64 v[6:7], s[42:43], 0, v[4:5]
	v_mov_b32_e32 v2, v154
	v_lshl_add_u64 v[8:9], s[14:15], 0, v[4:5]
	v_add_co_u32_e32 v6, vcc, s0, v8
	v_bfe_u32 v43, v42, 4, 2
	s_nop 0
	v_addc_co_u32_e32 v7, vcc, 0, v9, vcc
	v_mov_b32_e32 v14, v155
	v_mov_b32_e32 v15, v168
	v_mov_b32_e32 v16, v169
	v_mov_b32_e32 v17, v171
	v_and_b32_e32 v18, 0xffffffc0, v42
	v_lshl_or_b32 v104, v43, 3, v18
	v_lshl_add_u64 v[18:19], s[16:17], 0, v[4:5]
	v_lshl_add_u64 v[20:21], s[36:37], 0, v[4:5]
	v_lshl_add_u64 v[4:5], s[40:41], 0, v[4:5]
	v_mov_b32_e32 v18, v240
	s_nop 0
	v_mov_b32_e32 v19, v241
	s_nop 0
	v_mov_b32_e32 v20, v242
	v_lshrrev_b32_e32 v30, 1, v42
	v_and_b32_e32 v31, 1, v42
	v_lshlrev_b32_e32 v30, 6, v30
	v_lshl_or_b32 v30, v31, 2, v30
	v_and_b32_e32 v195, 15, v42
	v_add3_u32 v64, s20, v195, -3
	v_max_i32_e32 v64, 0, v64
	v_mul_u32_u24_e32 v64, 0x1200, v64
	v_lshl_add_u32 v64, v104, 1, v64
	v_add3_u32 v65, s20, v195, -2
	v_max_i32_e32 v65, 0, v65
	v_mul_u32_u24_e32 v65, 0x1200, v65
	v_lshl_add_u32 v65, v104, 1, v65
	v_add3_u32 v66, s20, v195, -1
	v_max_i32_e32 v66, 0, v66
	v_mul_u32_u24_e32 v66, 0x1200, v66
	v_lshl_add_u32 v66, v104, 1, v66
	v_add_u32_e32 v67, s20, v195
	v_mul_u32_u24_e32 v67, 0x1200, v67
	v_lshl_add_u32 v67, v104, 1, v67
	global_load_dwordx4 v[72:75], v64, s[88:89]
	global_load_dwordx4 v[76:79], v64, s[88:89] offset:64
	global_load_dwordx4 v[80:83], v65, s[88:89]
	global_load_dwordx4 v[84:87], v65, s[88:89] offset:64
	global_load_dwordx4 v[88:91], v66, s[88:89]
	global_load_dwordx4 v[92:95], v66, s[88:89] offset:64
	global_load_dwordx4 v[96:99], v67, s[88:89]
	global_load_dwordx4 v[100:103], v67, s[88:89] offset:64
	v_cmp_lt_u32_e32 vcc, 2, v195
	s_or_b64 s[0:1], s[22:23], vcc
	v_mov_b32_e32 v8, v3
	v_mov_b32_e32 v9, v3
	v_mov_b32_e32 v6, v3
	v_mov_b32_e32 v7, v3
	v_mov_b64_e32 v[12:13], v[8:9]
	v_mov_b64_e32 v[10:11], v[6:7]
	v_ashrrev_i32_e32 v105, 31, v104
	v_mul_f32_e64 v4, |v2|, s6
	v_exp_f32_e32 v21, v4
	v_max_f32_e64 v2, -v2, -v2
	v_max_f32_e32 v2, 0, v2
	ds_write2_b32 v30, v14, v15 offset1:2
	ds_write2_b32 v30, v16, v17 offset0:4 offset1:6
	v_add_f32_e32 v14, 1.0, v21
	v_add_f32_e32 v15, -1.0, v14
	v_frexp_mant_f32_e32 v16, v14
	v_cvt_f64_f32_e32 v[4:5], v14
	v_sub_f32_e32 v17, v15, v14
	v_frexp_exp_i32_f64_e32 v4, v[4:5]
	v_cmp_gt_f32_e32 vcc, s4, v16
	v_sub_f32_e32 v15, v21, v15
	v_add_f32_e32 v5, 1.0, v17
	v_subbrev_co_u32_e32 v4, vcc, 0, v4, vcc
	v_add_f32_e32 v5, v15, v5
	v_sub_u32_e32 v15, 0, v4
	v_ldexp_f32 v14, v14, v15
	v_add_f32_e32 v16, -1.0, v14
	v_add_f32_e32 v17, 1.0, v14
	v_ldexp_f32 v5, v5, v15
	v_add_f32_e32 v15, 1.0, v16
	v_add_f32_e32 v22, -1.0, v17
	v_sub_f32_e32 v15, v14, v15
	v_sub_f32_e32 v14, v14, v22
	v_add_f32_e32 v22, v5, v15
	v_add_f32_e32 v5, v5, v14
	v_add_f32_e32 v24, v17, v5
	v_rcp_f32_e32 v25, v24
	v_add_f32_e32 v15, v16, v22
	v_sub_f32_e32 v16, v15, v16
	v_sub_f32_e32 v14, v24, v17
	v_mul_f32_e32 v27, v15, v25
	v_sub_f32_e32 v26, v22, v16
	v_mul_f32_e32 v16, v24, v27
	v_sub_f32_e32 v5, v5, v14
	v_fma_f32 v22, v27, v24, -v16
	v_fmac_f32_e32 v22, v27, v5
	v_add_f32_e32 v14, v16, v22
	v_sub_f32_e32 v17, v15, v14
	v_mov_b32_e32 v23, v14
	v_pk_add_f32 v[14:15], v[14:15], v[16:17] neg_lo:[0,1] neg_hi:[0,1]
	v_cvt_f32_i32_e32 v4, v4
	v_pk_add_f32 v[14:15], v[14:15], v[22:23] neg_lo:[0,1] neg_hi:[0,1]
	v_cmp_neq_f32_e32 vcc, s3, v21
	v_add_f32_e32 v15, v26, v15
	v_add_f32_e32 v14, v14, v15
	v_add_f32_e32 v15, v17, v14
	v_mul_f32_e32 v23, v25, v15
	v_mul_f32_e32 v16, v24, v23
	v_sub_f32_e32 v17, v17, v15
	v_add_f32_e32 v28, v27, v23
	v_fma_f32 v22, v23, v24, -v16
	v_add_f32_e32 v26, v14, v17
	v_sub_f32_e32 v14, v28, v27
	v_fmac_f32_e32 v22, v23, v5
	v_sub_f32_e32 v5, v23, v14
	v_add_f32_e32 v14, v16, v22
	v_sub_f32_e32 v17, v15, v14
	v_mov_b32_e32 v23, v14
	v_pk_add_f32 v[14:15], v[14:15], v[16:17] neg_lo:[0,1] neg_hi:[0,1]
	s_nop 0
	v_pk_add_f32 v[14:15], v[14:15], v[22:23] neg_lo:[0,1] neg_hi:[0,1]
	s_nop 0
	v_add_f32_e32 v15, v26, v15
	v_add_f32_e32 v14, v14, v15
	v_add_f32_e32 v14, v17, v14
	v_mul_f32_e32 v14, v25, v14
	v_add_f32_e32 v5, v5, v14
	v_add_f32_e32 v14, v28, v5
	v_mul_f32_e32 v16, v14, v14
	v_sub_f32_e32 v17, v14, v28
	v_fmamk_f32 v22, v16, 0x3e9b6dac, v181
	v_sub_f32_e32 v17, v5, v17
	v_mul_f32_e32 v5, v14, v16
	v_fmaak_f32 v113, v16, v22, 0x3f2aaada
	v_ldexp_f32 v23, v17, 1
	v_pk_mul_f32 v[16:17], v[4:5], v[112:113]
	v_ldexp_f32 v15, v14, 1
	v_fma_f32 v14, v4, s5, -v16
	v_fmac_f32_e32 v14, 0xb102e308, v4
	v_pk_add_f32 v[4:5], v[16:17], v[14:15]
	v_mov_b32_e32 v22, v16
	v_sub_f32_e32 v26, v5, v15
	v_pk_add_f32 v[24:25], v[4:5], v[16:17] neg_lo:[0,1] neg_hi:[0,1]
	v_sub_f32_e32 v16, v17, v26
	v_add_f32_e32 v23, v23, v16
	v_pk_add_f32 v[16:17], v[4:5], v[22:23]
	v_mov_b32_e32 v15, v4
	v_mov_b32_e32 v25, v17
	v_pk_add_f32 v[28:29], v[14:15], v[24:25] neg_lo:[0,1] neg_hi:[0,1]
	v_pk_add_f32 v[14:15], v[14:15], v[24:25]
	v_mov_b32_e32 v27, v4
	v_pk_add_f32 v[24:25], v[14:15], v[4:5] op_sel:[1,0] op_sel_hi:[0,1] neg_lo:[0,1] neg_hi:[0,1]
	v_mov_b32_e32 v26, v23
	v_mov_b32_e32 v22, v17
	v_mov_b32_e32 v23, v15
	v_pk_mov_b32 v[4:5], v[4:5], v[24:25] op_sel:[1,0]
	v_pk_add_f32 v[16:17], v[16:17], v[24:25] op_sel_hi:[1,0] neg_lo:[0,1] neg_hi:[0,1]
	v_pk_add_f32 v[4:5], v[22:23], v[4:5] neg_lo:[0,1] neg_hi:[0,1]
	v_mov_b32_e32 v16, v28
	v_pk_add_f32 v[4:5], v[26:27], v[4:5] neg_lo:[0,1] neg_hi:[0,1]
	v_mov_b32_e32 v29, v15
	v_pk_add_f32 v[16:17], v[16:17], v[4:5]
	s_nop 0
	v_pk_add_f32 v[22:23], v[16:17], v[16:17] op_sel:[0,1] op_sel_hi:[1,0]
	s_nop 0
	v_pk_add_f32 v[14:15], v[14:15], v[22:23] op_sel:[1,0] op_sel_hi:[0,1]
	v_mov_b32_e32 v17, v14
	v_mov_b32_e32 v5, v22
	v_pk_add_f32 v[22:23], v[16:17], v[28:29] neg_lo:[0,1] neg_hi:[0,1]
	s_nop 0
	v_sub_f32_e32 v15, v16, v22
	v_pk_add_f32 v[4:5], v[4:5], v[22:23] neg_lo:[0,1] neg_hi:[0,1]
	v_sub_f32_e32 v15, v28, v15
	v_add_f32_e32 v4, v4, v15
	v_add_f32_e32 v4, v4, v5
	v_add_f32_e32 v4, v14, v4
	v_cndmask_b32_e32 v4, v185, v4, vcc
	v_cmp_ngt_f32_e32 vcc, -1.0, v21
	v_mov_b64_e32 v[16:17], v[8:9]
	v_mov_b64_e32 v[14:15], v[6:7]
	v_cndmask_b32_e32 v4, v186, v4, vcc
	v_cmp_neq_f32_e32 vcc, -1.0, v21
	s_nop 1
	v_cndmask_b32_e32 v4, v187, v4, vcc
	v_cmp_lt_f32_e64 vcc, |v21|, s2
	s_nop 1
	v_cndmask_b32_e32 v4, v4, v21, vcc
	v_add_f32_e32 v2, v2, v4
	v_mul_f32_e32 v21, 0xc1000000, v2
	ds_write2_b32 v30, v18, v19 offset0:8 offset1:10
	ds_write2_b32 v30, v20, v21 offset0:12 offset1:14
	s_and_saveexec_b64 s[2:3], s[0:1]
	s_cbranch_execz .LBB0_217
	v_add3_u32 v2, s20, -3, v195
	v_mov_b64_e32 v[4:5], s[88:89]
	v_mad_i64_i32 v[4:5], s[0:1], v2, s92, v[4:5]
	v_lshl_add_u64 v[4:5], v[104:105], 1, v[4:5]
.LBB0_217:
	s_or_b64 exec, exec, s[2:3]
	v_cmp_lt_u32_e32 vcc, 1, v195
	v_mov_b64_e32 v[20:21], v[8:9]
	s_or_b64 s[2:3], s[22:23], vcc
	v_mov_b64_e32 v[18:19], v[6:7]
	s_and_saveexec_b64 s[0:1], s[2:3]
	s_mov_b32 s7, 0xbe800000
	s_cbranch_execz .LBB0_219
	v_add3_u32 v2, s20, -2, v195
	v_mov_b64_e32 v[4:5], s[88:89]
	v_mad_i64_i32 v[4:5], s[2:3], v2, s92, v[4:5]
	v_lshl_add_u64 v[4:5], v[104:105], 1, v[4:5]
.LBB0_219:
	s_or_b64 exec, exec, s[0:1]
	v_or_b32_e32 v106, 32, v104
	v_cmp_eq_u32_e32 vcc, 0, v195
	s_xor_b64 s[0:1], s[22:23], -1
	s_and_b64 s[0:1], s[0:1], vcc
	v_ashrrev_i32_e32 v107, 31, v106
	s_and_saveexec_b64 s[2:3], s[0:1]
	s_xor_b64 s[0:1], exec, s[2:3]
	s_or_saveexec_b64 s[0:1], s[0:1]
	v_mov_b32_e32 v4, v3
	v_mov_b32_e32 v5, v3
	v_mov_b32_e32 v2, v3
	v_mov_b64_e32 v[28:29], v[4:5]
	v_mov_b64_e32 v[24:25], v[4:5]
	v_mov_b32_e32 v113, s20
	v_mov_b64_e32 v[26:27], v[2:3]
	v_mov_b64_e32 v[22:23], v[2:3]
	s_xor_b64 exec, exec, s[0:1]
	s_cbranch_execz .LBB0_221
	v_or_b32_e32 v113, s20, v195
	v_add_u32_e32 v2, -1, v113
	v_mov_b64_e32 v[4:5], s[88:89]
	v_mad_i64_i32 v[4:5], s[2:3], v2, s92, v[4:5]
	v_lshl_add_u64 v[4:5], v[104:105], 1, v[4:5]
.LBB0_221:
	s_or_b64 exec, exec, s[0:1]
	v_ashrrev_i32_e32 v4, 6, v42
	v_ashrrev_i32_e32 v5, 31, v4
	v_readlane_b32 s0, v244, 48
	v_and_b32_e32 v2, 63, v42
	v_lshlrev_b64 v[30:31], 13, v[4:5]
	v_readlane_b32 s1, v244, 49
	v_lshlrev_b32_e32 v2, 4, v2
	v_and_b32_e32 v5, 7, v42
	v_lshl_add_u64 v[30:31], s[0:1], 0, v[30:31]
	s_mov_b64 s[0:1], 0x10000
	v_lshl_add_u64 v[32:33], v[30:31], 0, s[0:1]
	v_lshl_add_u64 v[34:35], v[30:31], 0, v[2:3]
	v_lshl_add_u64 v[36:37], v[32:33], 0, v[2:3]
	v_or_b32_e32 v34, 0x1000, v2
	v_mov_b32_e32 v35, v3
	v_lshl_add_u64 v[36:37], v[30:31], 0, v[34:35]
	v_lshl_add_u64 v[34:35], v[32:33], 0, v[34:35]
	v_or_b32_e32 v34, 0x1400, v2
	v_mov_b32_e32 v35, v3
	v_lshl_add_u64 v[36:37], v[30:31], 0, v[34:35]
	v_lshl_add_u64 v[34:35], v[32:33], 0, v[34:35]
	v_or_b32_e32 v34, 0x1800, v2
	v_mov_b32_e32 v35, v3
	v_lshl_add_u64 v[36:37], v[30:31], 0, v[34:35]
	v_lshl_add_u64 v[34:35], v[32:33], 0, v[34:35]
	v_or_b32_e32 v34, 0x1c00, v2
	v_mov_b32_e32 v35, v3
	v_lshl_add_u64 v[30:31], v[30:31], 0, v[34:35]
	v_lshl_add_u64 v[32:33], v[32:33], 0, v[34:35]
	v_mov_b64_e32 v[30:31], s[88:89]
	v_lshrrev_b32_e32 v32, 4, v42
	v_bfe_u32 v33, v42, 4, 1
	v_mad_i64_i32 v[30:31], s[0:1], v113, s92, v[30:31]
	v_bitop3_b32 v34, v32, v5, 1 bitop3:0x6c
	v_bitop3_b32 v35, v33, v5, 2 bitop3:0x36
	v_bitop3_b32 v36, v33, v5, 4 bitop3:0x36
	v_bitop3_b32 v5, v33, v5, 6 bitop3:0x36
	v_lshl_add_u64 v[32:33], v[104:105], 1, v[30:31]
	v_lshl_add_u64 v[30:31], v[106:107], 1, v[30:31]
	v_lshlrev_b32_e32 v109, 4, v34
	v_lshlrev_b32_e32 v111, 4, v35
	v_lshlrev_b32_e32 v115, 4, v36
	s_nop 0
	s_movk_i32 s2, 0x780
	s_movk_i32 s3, 0xb80
	s_movk_i32 s4, 0xf80
	s_movk_i32 s5, 0x1380
	v_lshl_add_u32 v4, v4, 14, 0
	v_and_b32_e32 v108, 0x380, v2
	s_movk_i32 s6, 0x1780
	v_bitop3_b32 v110, v2, s2, v188 bitop3:0xc8
	v_bitop3_b32 v114, v2, s3, v189 bitop3:0xc8
	v_bitop3_b32 v116, v2, s4, v190 bitop3:0xc8
	v_lshlrev_b32_e32 v5, 4, v5
	v_bitop3_b32 v117, v2, s5, v191 bitop3:0xc8
	v_add3_u32 v108, v4, v108, v109
	v_add3_u32 v110, v4, v110, v111
	v_add3_u32 v114, v4, v114, v115
	v_add3_u32 v116, v4, v116, v5
	v_add3_u32 v109, v4, v117, v109
	s_movk_i32 s0, 0x1b80
	s_mov_b32 s2, 0xbfb8aa3b
	s_waitcnt vmcnt(24)
	ds_write_b128 v108, v[156:159] offset:16384
	ds_write_b128 v110, v[160:163] offset:16384
	ds_write_b128 v114, v[164:167] offset:16384
	ds_write_b128 v116, v[172:175] offset:16384
	ds_write_b128 v109, v[212:215] offset:16384
	ds_write_b128 v108, v[196:199] offset:24576
	ds_write_b128 v110, v[200:203] offset:24576
	ds_write_b128 v114, v[204:207] offset:24576
	ds_write_b128 v116, v[208:211] offset:24576
	ds_write_b128 v109, v[216:219] offset:24576
	v_bitop3_b32 v38, v2, s6, v192 bitop3:0xc8
	v_add3_u32 v38, v4, v38, v111
	ds_write_b128 v38, v[220:223] offset:16384
	ds_write_b128 v38, v[224:227] offset:24576
	v_bitop3_b32 v38, v2, s0, v193 bitop3:0xc8
	s_movk_i32 s0, 0x1f80
	v_bitop3_b32 v2, v2, s0, v194 bitop3:0xc8
	v_add3_u32 v38, v4, v38, v115
	v_add3_u32 v2, v4, v2, v5
	v_lshlrev_b32_e32 v5, 5, v104
	ds_write_b128 v38, v[228:231] offset:16384
	ds_write_b128 v38, v[232:235] offset:24576
	ds_write_b128 v2, v[236:239] offset:16384
	ds_write_b128 v2, v[248:251] offset:24576
	v_add_u32_e32 v2, 0, v5
	v_or_b32_e32 v38, 4, v5
	v_mov_b32_e32 v239, 0
	v_mov_b32_e32 v179, 1.0
	v_mov_b32_e32 v236, 1.0
	v_mov_b32_e32 v237, 1.0
	v_mov_b32_e32 v238, 1.0
	v_mov_b32_e32 v228, 1.0
	v_mov_b32_e32 v229, 1.0
	v_mov_b32_e32 v230, 1.0
	v_mov_b32_e32 v231, 1.0
	v_mov_b32_e32 v220, 1.0
	v_mov_b32_e32 v221, 1.0
	v_mov_b32_e32 v222, 1.0
	v_mov_b32_e32 v223, 1.0
	v_mov_b32_e32 v171, 1.0
	v_mov_b32_e32 v213, 1.0
	v_mov_b32_e32 v214, 1.0
	v_mov_b32_e32 v215, 1.0
	v_mov_b32_e32 v240, 0
	v_mov_b32_e32 v241, 0
	s_waitcnt lgkmcnt(0)
	s_barrier
	v_add_u32_e32 v196, 0, v38
	ds_read2_b32 v[38:39], v2 offset0:10 offset1:12
	ds_read2_b32 v[40:41], v196 offset0:10 offset1:12
	ds_read_b32 v44, v2 offset:56
	ds_read_b32 v45, v196 offset:56
	s_mov_b32 s0, 0x3fb8aa3b
	s_waitcnt lgkmcnt(3)
	v_mov_b32_e32 v46, v38
	v_or_b32_e32 v38, 64, v5
	s_waitcnt lgkmcnt(2)
	v_mov_b32_e32 v47, v40
	v_mov_b32_e32 v40, v39
	v_add_u32_e32 v197, 0, v38
	v_or_b32_e32 v38, 0x44, v5
	v_pk_mul_f32 v[110:111], v[40:41], s[2:3] op_sel_hi:[1,0]
	v_add_u32_e32 v198, 0, v38
	ds_read2_b32 v[38:39], v197 offset0:10 offset1:12
	ds_read2_b32 v[40:41], v198 offset0:10 offset1:12
	v_pk_mul_f32 v[108:109], v[46:47], s[2:3] op_sel_hi:[1,0]
	s_waitcnt lgkmcnt(2)
	v_pk_mul_f32 v[114:115], v[44:45], s[0:1] op_sel_hi:[1,0]
	ds_read_b32 v44, v197 offset:56
	ds_read_b32 v45, v198 offset:56
	s_waitcnt lgkmcnt(3)
	v_mov_b32_e32 v46, v38
	v_or_b32_e32 v38, 0x80, v5
	s_waitcnt lgkmcnt(2)
	v_mov_b32_e32 v47, v40
	v_mov_b32_e32 v40, v39
	v_add_u32_e32 v199, 0, v38
	v_or_b32_e32 v38, 0x84, v5
	v_pk_mul_f32 v[118:119], v[40:41], s[2:3] op_sel_hi:[1,0]
	v_add_u32_e32 v200, 0, v38
	ds_read2_b32 v[38:39], v199 offset0:10 offset1:12
	ds_read2_b32 v[40:41], v200 offset0:10 offset1:12
	v_pk_mul_f32 v[116:117], v[46:47], s[2:3] op_sel_hi:[1,0]
	s_waitcnt lgkmcnt(2)
	v_pk_mul_f32 v[120:121], v[44:45], s[0:1] op_sel_hi:[1,0]
	ds_read_b32 v44, v199 offset:56
	ds_read_b32 v45, v200 offset:56
	s_waitcnt lgkmcnt(3)
	v_mov_b32_e32 v46, v38
	v_or_b32_e32 v38, 0xc0, v5
	s_waitcnt lgkmcnt(2)
	v_mov_b32_e32 v47, v40
	v_mov_b32_e32 v40, v39
	v_add_u32_e32 v201, 0, v38
	v_or_b32_e32 v38, 0xc4, v5
	v_pk_mul_f32 v[124:125], v[40:41], s[2:3] op_sel_hi:[1,0]
	v_add_u32_e32 v202, 0, v38
	ds_read2_b32 v[38:39], v201 offset0:10 offset1:12
	ds_read2_b32 v[40:41], v202 offset0:10 offset1:12
	v_pk_mul_f32 v[122:123], v[46:47], s[2:3] op_sel_hi:[1,0]
	s_waitcnt lgkmcnt(2)
	v_pk_mul_f32 v[126:127], v[44:45], s[0:1] op_sel_hi:[1,0]
	ds_read_b32 v44, v201 offset:56
	ds_read_b32 v45, v202 offset:56
	s_waitcnt lgkmcnt(3)
	v_mov_b32_e32 v46, v38
	v_lshlrev_b32_e32 v38, 5, v106
	s_waitcnt lgkmcnt(2)
	v_mov_b32_e32 v47, v40
	v_mov_b32_e32 v40, v39
	v_add_u32_e32 v203, 0, v38
	v_or_b32_e32 v38, 0x404, v5
	v_pk_mul_f32 v[130:131], v[40:41], s[2:3] op_sel_hi:[1,0]
	v_add_u32_e32 v204, 0, v38
	ds_read2_b32 v[38:39], v203 offset0:10 offset1:12
	ds_read2_b32 v[40:41], v204 offset0:10 offset1:12
	v_pk_mul_f32 v[128:129], v[46:47], s[2:3] op_sel_hi:[1,0]
	s_waitcnt lgkmcnt(2)
	v_pk_mul_f32 v[132:133], v[44:45], s[0:1] op_sel_hi:[1,0]
	ds_read_b32 v44, v203 offset:56
	ds_read_b32 v45, v204 offset:56
	s_waitcnt lgkmcnt(3)
	v_mov_b32_e32 v46, v38
	v_or_b32_e32 v38, 0x440, v5
	s_waitcnt lgkmcnt(2)
	v_mov_b32_e32 v47, v40
	v_mov_b32_e32 v40, v39
	v_add_u32_e32 v205, 0, v38
	v_or_b32_e32 v38, 0x444, v5
	v_pk_mul_f32 v[136:137], v[40:41], s[2:3] op_sel_hi:[1,0]
	v_add_u32_e32 v206, 0, v38
	ds_read2_b32 v[38:39], v205 offset0:10 offset1:12
	ds_read2_b32 v[40:41], v206 offset0:10 offset1:12
	v_pk_mul_f32 v[134:135], v[46:47], s[2:3] op_sel_hi:[1,0]
	s_waitcnt lgkmcnt(2)
	v_pk_mul_f32 v[138:139], v[44:45], s[0:1] op_sel_hi:[1,0]
	ds_read_b32 v44, v205 offset:56
	ds_read_b32 v45, v206 offset:56
	s_waitcnt lgkmcnt(3)
	v_mov_b32_e32 v46, v38
	v_or_b32_e32 v38, 0x480, v5
	s_waitcnt lgkmcnt(2)
	v_mov_b32_e32 v47, v40
	v_mov_b32_e32 v40, v39
	v_add_u32_e32 v207, 0, v38
	v_or_b32_e32 v38, 0x484, v5
	v_pk_mul_f32 v[142:143], v[40:41], s[2:3] op_sel_hi:[1,0]
	v_add_u32_e32 v208, 0, v38
	ds_read2_b32 v[38:39], v207 offset0:10 offset1:12
	ds_read2_b32 v[40:41], v208 offset0:10 offset1:12
	v_pk_mul_f32 v[140:141], v[46:47], s[2:3] op_sel_hi:[1,0]
	s_waitcnt lgkmcnt(2)
	v_pk_mul_f32 v[144:145], v[44:45], s[0:1] op_sel_hi:[1,0]
	ds_read_b32 v44, v207 offset:56
	ds_read_b32 v45, v208 offset:56
	s_waitcnt lgkmcnt(3)
	v_mov_b32_e32 v46, v38
	v_or_b32_e32 v38, 0x4c0, v5
	s_waitcnt lgkmcnt(2)
	v_mov_b32_e32 v47, v40
	v_mov_b32_e32 v40, v39
	v_add_u32_e32 v209, 0, v38
	v_or_b32_e32 v5, 0x4c4, v5
	v_pk_mul_f32 v[148:149], v[40:41], s[2:3] op_sel_hi:[1,0]
	v_add_u32_e32 v210, 0, v5
	ds_read2_b32 v[38:39], v209 offset0:10 offset1:12
	ds_read2_b32 v[40:41], v210 offset0:10 offset1:12
	s_waitcnt lgkmcnt(2)
	v_pk_mul_f32 v[150:151], v[44:45], s[0:1] op_sel_hi:[1,0]
	ds_read_b32 v44, v209 offset:56
	ds_read_b32 v45, v210 offset:56
	v_pk_mul_f32 v[146:147], v[46:47], s[2:3] op_sel_hi:[1,0]
	s_waitcnt lgkmcnt(3)
	v_mov_b32_e32 v46, v38
	v_lshlrev_b32_e32 v5, 1, v195
	v_and_b32_e32 v38, 3, v42
	s_waitcnt lgkmcnt(2)
	v_mov_b32_e32 v47, v40
	v_mov_b32_e32 v40, v39
	v_and_or_b32 v5, v5, 24, v38
	v_lshrrev_b32_e32 v38, 1, v42
	v_bfe_u32 v39, v42, 1, 3
	v_bitop3_b32 v38, v43, v38, 7 bitop3:0x78
	v_lshl_add_u32 v4, v5, 7, v4
	v_bitop3_b32 v5, v43, v39, 4 bitop3:0x36
	v_lshlrev_b32_e32 v38, 4, v38
	v_lshlrev_b32_e32 v5, 4, v5
	v_pk_mul_f32 v[152:153], v[46:47], s[2:3] op_sel_hi:[1,0]
	v_pk_mul_f32 v[154:155], v[40:41], s[2:3] op_sel_hi:[1,0]
	s_waitcnt lgkmcnt(0)
	v_pk_mul_f32 v[156:157], v[44:45], s[0:1] op_sel_hi:[1,0]
	s_mov_b32 s2, 0
	v_add_u32_e32 v211, v4, v38
	v_add_u32_e32 v212, v4, v5
	v_mov_b32_e32 v242, 0
	v_mov_b32_e32 v232, 0
	v_mov_b32_e32 v233, 0
	v_mov_b32_e32 v234, 0
	v_mov_b32_e32 v235, 0
	v_mov_b32_e32 v224, 0
	v_mov_b32_e32 v225, 0
	v_mov_b32_e32 v226, 0
	v_mov_b32_e32 v227, 0
	v_mov_b32_e32 v216, 0
	v_mov_b32_e32 v217, 0
	v_mov_b32_e32 v218, 0
	v_mov_b32_e32 v219, 0
	s_waitcnt vmcnt(0)
	v_mov_b64_e32 v[34:35], v[96:97]
	v_mov_b64_e32 v[36:37], v[98:99]
	v_mov_b64_e32 v[30:31], v[100:101]
	v_mov_b64_e32 v[32:33], v[102:103]
	v_cmp_lt_u32_e32 vcc, 2, v195
	s_or_b64 s[10:11], s[22:23], vcc
	s_and_saveexec_b64 s[12:13], s[10:11]
	v_mov_b64_e32 v[14:15], v[72:73]
	v_mov_b64_e32 v[16:17], v[74:75]
	v_mov_b64_e32 v[10:11], v[76:77]
	v_mov_b64_e32 v[12:13], v[78:79]
	s_mov_b64 exec, s[12:13]
	v_cmp_lt_u32_e32 vcc, 1, v195
	s_or_b64 s[10:11], s[22:23], vcc
	s_and_saveexec_b64 s[12:13], s[10:11]
	v_mov_b64_e32 v[18:19], v[80:81]
	v_mov_b64_e32 v[20:21], v[82:83]
	v_mov_b64_e32 v[6:7], v[84:85]
	v_mov_b64_e32 v[8:9], v[86:87]
	s_mov_b64 exec, s[12:13]
	v_cmp_lt_u32_e32 vcc, 0, v195
	s_or_b64 s[10:11], s[22:23], vcc
	s_and_saveexec_b64 s[12:13], s[10:11]
	v_mov_b64_e32 v[22:23], v[88:89]
	v_mov_b64_e32 v[24:25], v[90:91]
	v_mov_b64_e32 v[26:27], v[92:93]
	v_mov_b64_e32 v[28:29], v[94:95]
	s_mov_b64 exec, s[12:13]
	s_branch .LBB0_223
